# moba_pre: all 64 k_mean token loads in flight together; V tile loads for the V^T transpose issued at item start
# baseline (speedup 1.0000x reference)
.LBB0_163:
	s_ashr_i32 s12, s10, 7
	s_bfe_u32 s14, s10, 0x50002
	s_lshl_b32 s0, s12, 13
	s_lshl_b32 s11, s14, 8
	s_or_b32 s13, s11, s0
	s_and_b32 s15, s10, 3
	v_add_u32_e32 v13, s13, v1
	s_waitcnt vmcnt(12)
	v_mov_b64_e32 v[16:17], s[88:89]
	v_mad_i64_i32 v[14:15], s[0:1], v13, s72, v[16:17]
	s_lshl_b32 s20, s15, 8
	v_mov_b32_e32 v13, v3
	v_lshl_add_u64 v[14:15], v[14:15], 0, s[20:21]
	v_lshl_add_u64 v[14:15], v[14:15], 0, v[12:13]
	s_mov_b64 s[16:17], 0x1000
	s_mov_b64 s[18:19], 0x1400
	v_lshl_add_u64 v[68:69], v[14:15], 0, s[16:17]
	v_lshl_add_u64 v[56:57], v[14:15], 0, s[18:19]
	v_add_co_u32_e32 v70, vcc, s3, v14
	v_add_u32_e32 v14, s13, v60
	s_nop 0
	v_addc_co_u32_e32 v71, vcc, 0, v15, vcc
	v_mad_i64_i32 v[14:15], s[0:1], v14, s72, v[16:17]
	v_lshl_add_u64 v[14:15], v[14:15], 0, s[20:21]
	v_lshl_add_u64 v[14:15], v[14:15], 0, v[12:13]
	v_lshl_add_u64 v[72:73], v[14:15], 0, s[16:17]
	v_lshl_add_u64 v[48:49], v[14:15], 0, s[18:19]
	v_add_co_u32_e32 v54, vcc, s3, v14
	v_add_u32_e32 v14, s13, v61
	s_nop 0
	v_addc_co_u32_e32 v55, vcc, 0, v15, vcc
	v_mad_i64_i32 v[14:15], s[0:1], v14, s72, v[16:17]
	v_lshl_add_u64 v[14:15], v[14:15], 0, s[20:21]
	v_lshl_add_u64 v[14:15], v[14:15], 0, v[12:13]
	v_lshl_add_u64 v[52:53], v[14:15], 0, s[16:17]
	v_lshl_add_u64 v[44:45], v[14:15], 0, s[18:19]
	v_add_co_u32_e32 v50, vcc, s3, v14
	v_add_u32_e32 v14, s13, v62
	s_nop 0
	v_addc_co_u32_e32 v51, vcc, 0, v15, vcc
	v_mad_i64_i32 v[14:15], s[0:1], v14, s72, v[16:17]
	v_lshl_add_u64 v[14:15], v[14:15], 0, s[20:21]
	v_lshl_add_u64 v[14:15], v[14:15], 0, v[12:13]
	v_lshl_add_u64 v[46:47], v[14:15], 0, s[16:17]
	v_lshl_add_u64 v[36:37], v[14:15], 0, s[18:19]
	v_add_co_u32_e32 v42, vcc, s3, v14
	v_add_u32_e32 v14, s13, v63
	s_nop 0
	v_addc_co_u32_e32 v43, vcc, 0, v15, vcc
	v_mad_i64_i32 v[14:15], s[0:1], v14, s72, v[16:17]
	v_lshl_add_u64 v[14:15], v[14:15], 0, s[20:21]
	v_lshl_add_u64 v[14:15], v[14:15], 0, v[12:13]
	v_lshl_add_u64 v[40:41], v[14:15], 0, s[16:17]
	s_waitcnt vmcnt(9)
	v_lshl_add_u64 v[30:31], v[14:15], 0, s[18:19]
	v_add_co_u32_e32 v38, vcc, s3, v14
	v_add_u32_e32 v14, s13, v64
	s_waitcnt lgkmcnt(0)
	s_barrier
	s_mov_b64 s[86:87], vcc
	s_mov_b32 s82, 0
	v_add_u32_e32 v186, s82, v0
	v_ashrrev_i32_e32 v187, 4, v186
	v_mov_b64_e32 v[188:189], s[88:89]
	v_add_u32_e32 v186, 0x200, v186
	v_add_u32_e32 v190, s13, v187
	v_ashrrev_i32_e32 v186, 4, v186
	v_mad_i64_i32 v[190:191], s[80:81], v190, s72, v[188:189]
	v_add_u32_e32 v192, s13, v186
	v_lshl_add_u64 v[190:191], v[190:191], 0, s[20:21]
	v_mad_i64_i32 v[188:189], s[80:81], v192, s72, v[188:189]
	v_lshl_add_u64 v[190:191], v[190:191], 0, v[2:3]
	v_lshl_add_u64 v[188:189], v[188:189], 0, s[20:21]
	v_add_co_u32_e32 v190, vcc, 0x1000, v190
	v_lshl_add_u64 v[188:189], v[188:189], 0, v[2:3]
	s_nop 0
	v_addc_co_u32_e32 v191, vcc, 0, v191, vcc
	v_add_co_u32_e32 v192, vcc, 0x1000, v188
	s_addk_i32 s82, 0x400
	s_nop 0
	v_addc_co_u32_e32 v193, vcc, 0, v189, vcc
	global_load_dwordx4 v[236:239], v[190:191], off offset:2048
	global_load_dwordx4 v[240:243], v[192:193], off offset:2048
	v_add_u32_e32 v186, s82, v0
	v_ashrrev_i32_e32 v187, 4, v186
	v_mov_b64_e32 v[188:189], s[88:89]
	v_add_u32_e32 v186, 0x200, v186
	v_add_u32_e32 v190, s13, v187
	v_ashrrev_i32_e32 v186, 4, v186
	v_mad_i64_i32 v[190:191], s[80:81], v190, s72, v[188:189]
	v_add_u32_e32 v192, s13, v186
	v_lshl_add_u64 v[190:191], v[190:191], 0, s[20:21]
	v_mad_i64_i32 v[188:189], s[80:81], v192, s72, v[188:189]
	v_lshl_add_u64 v[190:191], v[190:191], 0, v[2:3]
	v_lshl_add_u64 v[188:189], v[188:189], 0, s[20:21]
	v_add_co_u32_e32 v190, vcc, 0x1000, v190
	v_lshl_add_u64 v[188:189], v[188:189], 0, v[2:3]
	s_nop 0
	v_addc_co_u32_e32 v191, vcc, 0, v191, vcc
	v_add_co_u32_e32 v192, vcc, 0x1000, v188
	s_addk_i32 s82, 0x400
	s_nop 0
	v_addc_co_u32_e32 v193, vcc, 0, v189, vcc
	global_load_dwordx4 v[244:247], v[190:191], off offset:2048
	global_load_dwordx4 v[248:251], v[192:193], off offset:2048
	v_add_u32_e32 v186, s82, v0
	v_ashrrev_i32_e32 v187, 4, v186
	v_mov_b64_e32 v[188:189], s[88:89]
	v_add_u32_e32 v186, 0x200, v186
	v_add_u32_e32 v190, s13, v187
	v_ashrrev_i32_e32 v186, 4, v186
	v_mad_i64_i32 v[190:191], s[80:81], v190, s72, v[188:189]
	v_add_u32_e32 v192, s13, v186
	v_lshl_add_u64 v[190:191], v[190:191], 0, s[20:21]
	v_mad_i64_i32 v[188:189], s[80:81], v192, s72, v[188:189]
	v_lshl_add_u64 v[190:191], v[190:191], 0, v[2:3]
	v_lshl_add_u64 v[188:189], v[188:189], 0, s[20:21]
	v_add_co_u32_e32 v190, vcc, 0x1000, v190
	v_lshl_add_u64 v[188:189], v[188:189], 0, v[2:3]
	s_nop 0
	v_addc_co_u32_e32 v191, vcc, 0, v191, vcc
	v_add_co_u32_e32 v192, vcc, 0x1000, v188
	s_addk_i32 s82, 0x400
	s_nop 0
	v_addc_co_u32_e32 v193, vcc, 0, v189, vcc
	global_load_dwordx4 v[160:163], v[190:191], off offset:2048
	global_load_dwordx4 v[164:167], v[192:193], off offset:2048
	v_add_u32_e32 v186, s82, v0
	v_ashrrev_i32_e32 v187, 4, v186
	v_mov_b64_e32 v[188:189], s[88:89]
	v_add_u32_e32 v186, 0x200, v186
	v_add_u32_e32 v190, s13, v187
	v_ashrrev_i32_e32 v186, 4, v186
	v_mad_i64_i32 v[190:191], s[80:81], v190, s72, v[188:189]
	v_add_u32_e32 v192, s13, v186
	v_lshl_add_u64 v[190:191], v[190:191], 0, s[20:21]
	v_mad_i64_i32 v[188:189], s[80:81], v192, s72, v[188:189]
	v_lshl_add_u64 v[190:191], v[190:191], 0, v[2:3]
	v_lshl_add_u64 v[188:189], v[188:189], 0, s[20:21]
	v_add_co_u32_e32 v190, vcc, 0x1000, v190
	v_lshl_add_u64 v[188:189], v[188:189], 0, v[2:3]
	s_nop 0
	v_addc_co_u32_e32 v191, vcc, 0, v191, vcc
	v_add_co_u32_e32 v192, vcc, 0x1000, v188
	s_addk_i32 s82, 0x400
	s_nop 0
	v_addc_co_u32_e32 v193, vcc, 0, v189, vcc
	global_load_dwordx4 v[168:171], v[190:191], off offset:2048
	global_load_dwordx4 v[140:143], v[192:193], off offset:2048
	s_mov_b64 vcc, s[86:87]
	global_load_ushort v67, v[70:71], off
	global_load_ushort v74, v[68:69], off offset:32
	global_load_ushort v75, v[70:71], off offset:1024
	global_load_ushort v76, v[54:55], off
	global_load_ushort v77, v[72:73], off offset:32
	global_load_ushort v78, v[54:55], off offset:1024
	global_load_ushort v79, v[48:49], off offset:32
	global_load_ushort v80, v[56:57], off offset:32
	v_addc_co_u32_e32 v39, vcc, 0, v15, vcc
	v_mad_i64_i32 v[14:15], s[0:1], v14, s72, v[16:17]
	v_lshl_add_u64 v[14:15], v[14:15], 0, s[20:21]
	v_lshl_add_u64 v[14:15], v[14:15], 0, v[12:13]
	s_waitcnt vmcnt(16)
	v_lshl_add_u64 v[34:35], v[14:15], 0, s[16:17]
	v_lshl_add_u64 v[22:23], v[14:15], 0, s[18:19]
	v_add_co_u32_e32 v28, vcc, s3, v14
	v_add_u32_e32 v14, s13, v65
	s_nop 0
	v_addc_co_u32_e32 v29, vcc, 0, v15, vcc
	v_mad_i64_i32 v[14:15], s[0:1], v14, s72, v[16:17]
	v_lshl_add_u64 v[14:15], v[14:15], 0, s[20:21]
	v_lshl_add_u64 v[18:19], v[14:15], 0, v[12:13]
	v_lshl_add_u64 v[26:27], v[18:19], 0, s[16:17]
	v_lshl_add_u64 v[14:15], v[18:19], 0, s[18:19]
	v_add_co_u32_e32 v24, vcc, s3, v18
	v_add_u32_e32 v18, s13, v66
	v_mad_i64_i32 v[16:17], s[0:1], v18, s72, v[16:17]
	v_lshl_add_u64 v[16:17], v[16:17], 0, s[20:21]
	v_addc_co_u32_e32 v25, vcc, 0, v19, vcc
	v_lshl_add_u64 v[20:21], v[16:17], 0, v[12:13]
	v_lshl_add_u64 v[18:19], v[20:21], 0, s[16:17]
	v_lshl_add_u64 v[16:17], v[20:21], 0, s[18:19]
	v_add_co_u32_e32 v20, vcc, s3, v20
	global_load_ushort v81, v[50:51], off
	global_load_ushort v82, v[52:53], off offset:32
	global_load_ushort v83, v[50:51], off offset:1024
	global_load_ushort v84, v[42:43], off
	global_load_ushort v85, v[46:47], off offset:32
	global_load_ushort v86, v[42:43], off offset:1024
	global_load_ushort v87, v[36:37], off offset:32
	global_load_ushort v88, v[44:45], off offset:32
	global_load_ushort v89, v[38:39], off
	global_load_ushort v90, v[40:41], off offset:32
	global_load_ushort v91, v[38:39], off offset:1024
	global_load_ushort v92, v[28:29], off
	global_load_ushort v93, v[34:35], off offset:32
	global_load_ushort v94, v[28:29], off offset:1024
	global_load_ushort v95, v[22:23], off offset:32
	global_load_ushort v96, v[30:31], off offset:32
	v_addc_co_u32_e32 v21, vcc, 0, v21, vcc
	global_load_ushort v13, v[24:25], off
	global_load_ushort v97, v[26:27], off offset:32
	global_load_ushort v98, v[24:25], off offset:1024
	global_load_ushort v99, v[18:19], off offset:32
	global_load_ushort v100, v[16:17], off offset:32
	global_load_ushort v101, v[20:21], off
	global_load_ushort v102, v[14:15], off offset:32
	global_load_ushort v103, v[20:21], off offset:1024
	s_and_b32 s0, s9, 3
	s_lshl_b32 s0, s0, 8
	v_mov_b32_e32 v32, s0
	s_mov_b32 s0, 0x6dc9c883
	s_mov_b32 s1, 0x3fc45f30
	v_mov_b32_e32 v33, v3
	s_lshl_b32 s16, s15, 7
	s_waitcnt vmcnt(31)
	v_lshlrev_b32_e32 v67, 16, v67
	s_waitcnt vmcnt(30)
	v_lshlrev_b32_e32 v104, 16, v74
	v_add_u32_e32 v74, s11, v1
	v_cvt_f32_i32_e32 v74, v74
	s_waitcnt vmcnt(29)
	v_lshlrev_b32_e32 v105, 16, v75
	s_waitcnt vmcnt(28)
	v_lshlrev_b32_e32 v106, 16, v76
	s_waitcnt vmcnt(27)
	v_lshlrev_b32_e32 v107, 16, v77
	v_mul_f32_e32 v74, v9, v74
	v_cvt_f64_f32_e32 v[74:75], v74
	v_mul_f64 v[76:77], v[74:75], s[0:1]
	v_rndne_f64_e32 v[76:77], v[76:77]
	v_fma_f64 v[74:75], v[74:75], s[0:1], -v[76:77]
	v_cvt_f32_f64_e32 v74, v[74:75]
	v_sin_f32_e32 v75, v74
	v_cos_f32_e32 v74, v74
	s_waitcnt vmcnt(24)
	v_lshlrev_b32_e32 v80, 16, v80
	v_lshlrev_b32_e32 v79, 16, v79
	v_lshlrev_b32_e32 v78, 16, v78
	s_waitcnt vmcnt(23)
	v_lshlrev_b32_e32 v81, 16, v81
	s_waitcnt vmcnt(22)
	v_lshlrev_b32_e32 v82, 16, v82
	s_waitcnt vmcnt(21)
	v_lshlrev_b32_e32 v83, 16, v83
	s_waitcnt vmcnt(20)
	v_lshlrev_b32_e32 v84, 16, v84
	s_waitcnt vmcnt(19)
	v_lshlrev_b32_e32 v85, 16, v85
	s_waitcnt vmcnt(18)
	v_lshlrev_b32_e32 v86, 16, v86
	s_waitcnt vmcnt(17)
	v_lshlrev_b32_e32 v87, 16, v87
	s_waitcnt vmcnt(16)
	v_lshlrev_b32_e32 v88, 16, v88
	s_waitcnt vmcnt(3)
	v_lshlrev_b32_e32 v77, 16, v100
	v_mul_f32_e32 v100, v75, v104
	v_fma_f32 v100, v74, v67, -v100
	v_mul_f32_e32 v67, v75, v67
	v_fmac_f32_e32 v67, v74, v104
	v_cvt_pk_bf16_f32 v67, v67, s0
	global_store_short v[68:69], v67, off offset:32
	v_add_u32_e32 v68, s11, v60
	v_cvt_f32_i32_e32 v68, v68
	v_mul_f32_e32 v67, v75, v80
	v_fma_f32 v67, v74, v105, -v67
	v_cvt_pk_bf16_f32 v100, v100, s0
	v_mul_f32_e32 v68, v9, v68
	v_cvt_pk_bf16_f32 v67, v67, s0
	v_cvt_f64_f32_e32 v[68:69], v68
	global_store_short v[70:71], v100, off
	global_store_short v[70:71], v67, off offset:1024
	v_mul_f64 v[70:71], v[68:69], s[0:1]
	v_rndne_f64_e32 v[70:71], v[70:71]
	v_fma_f64 v[68:69], v[68:69], s[0:1], -v[70:71]
	v_cvt_f32_f64_e32 v68, v[68:69]
	v_sin_f32_e32 v69, v68
	v_mul_f32_e32 v67, v75, v105
	v_cos_f32_e32 v68, v68
	v_fmac_f32_e32 v67, v74, v80
	v_cvt_pk_bf16_f32 v67, v67, s0
	global_store_short v[56:57], v67, off offset:32
	v_mul_f32_e32 v56, v69, v107
	v_fma_f32 v56, v68, v106, -v56
	v_cvt_pk_bf16_f32 v56, v56, s0
	global_store_short v[54:55], v56, off
	v_mul_f32_e32 v56, v69, v106
	v_fmac_f32_e32 v56, v68, v107
	v_add_u32_e32 v57, s11, v61
	v_cvt_pk_bf16_f32 v56, v56, s0
	v_cvt_f32_i32_e32 v57, v57
	global_store_short v[72:73], v56, off offset:32
	v_mul_f32_e32 v56, v69, v79
	v_fma_f32 v56, v68, v78, -v56
	v_cvt_pk_bf16_f32 v56, v56, s0
	global_store_short v[54:55], v56, off offset:1024
	v_mul_f32_e32 v54, v9, v57
	v_cvt_f64_f32_e32 v[54:55], v54
	v_mul_f64 v[56:57], v[54:55], s[0:1]
	v_rndne_f64_e32 v[56:57], v[56:57]
	v_fma_f64 v[54:55], v[54:55], s[0:1], -v[56:57]
	v_cvt_f32_f64_e32 v54, v[54:55]
	v_sin_f32_e32 v55, v54
	v_mul_f32_e32 v67, v68, v79
	v_cos_f32_e32 v54, v54
	v_fmac_f32_e32 v67, v69, v78
	v_cvt_pk_bf16_f32 v56, v67, s0
	global_store_short v[48:49], v56, off offset:32
	v_mul_f32_e32 v48, v55, v82
	v_fma_f32 v48, v54, v81, -v48
	v_cvt_pk_bf16_f32 v48, v48, s0
	global_store_short v[50:51], v48, off
	v_mul_f32_e32 v48, v54, v82
	v_fmac_f32_e32 v48, v55, v81
	v_add_u32_e32 v49, s11, v62
	v_cvt_pk_bf16_f32 v48, v48, s0
	v_cvt_f32_i32_e32 v49, v49
	global_store_short v[52:53], v48, off offset:32
	v_mul_f32_e32 v48, v55, v88
	v_fma_f32 v48, v54, v83, -v48
	v_cvt_pk_bf16_f32 v48, v48, s0
	global_store_short v[50:51], v48, off offset:1024
	v_mul_f32_e32 v48, v9, v49
	v_cvt_f64_f32_e32 v[48:49], v48
	v_mul_f64 v[50:51], v[48:49], s[0:1]
	v_rndne_f64_e32 v[50:51], v[50:51]
	v_fma_f64 v[48:49], v[48:49], s[0:1], -v[50:51]
	v_cvt_f32_f64_e32 v48, v[48:49]
	v_sin_f32_e32 v49, v48
	v_mul_f32_e32 v52, v54, v88
	v_cos_f32_e32 v48, v48
	v_fmac_f32_e32 v52, v55, v83
	v_cvt_pk_bf16_f32 v50, v52, s0
	global_store_short v[44:45], v50, off offset:32
	v_mul_f32_e32 v44, v49, v85
	v_fma_f32 v44, v48, v84, -v44
	v_cvt_pk_bf16_f32 v44, v44, s0
	global_store_short v[42:43], v44, off
	v_mul_f32_e32 v44, v48, v85
	v_fmac_f32_e32 v44, v49, v84
	v_add_u32_e32 v45, s11, v63
	v_cvt_pk_bf16_f32 v44, v44, s0
	v_cvt_f32_i32_e32 v45, v45
	global_store_short v[46:47], v44, off offset:32
	v_mul_f32_e32 v44, v49, v87
	v_fma_f32 v44, v48, v86, -v44
	v_cvt_pk_bf16_f32 v44, v44, s0
	global_store_short v[42:43], v44, off offset:1024
	v_mul_f32_e32 v42, v9, v45
	v_cvt_f64_f32_e32 v[42:43], v42
	v_mul_f64 v[44:45], v[42:43], s[0:1]
	v_rndne_f64_e32 v[44:45], v[44:45]
	v_fma_f64 v[42:43], v[42:43], s[0:1], -v[44:45]
	v_cvt_f32_f64_e32 v42, v[42:43]
	v_sin_f32_e32 v43, v42
	v_mul_f32_e32 v46, v48, v87
	v_cos_f32_e32 v42, v42
	v_fmac_f32_e32 v46, v49, v86
	v_lshlrev_b32_e32 v90, 16, v90
	v_cvt_pk_bf16_f32 v44, v46, s0
	v_lshlrev_b32_e32 v89, 16, v89
	global_store_short v[36:37], v44, off offset:32
	v_mul_f32_e32 v36, v43, v90
	v_fma_f32 v36, v42, v89, -v36
	v_cvt_pk_bf16_f32 v36, v36, s0
	global_store_short v[38:39], v36, off
	v_mul_f32_e32 v36, v42, v90
	v_fmac_f32_e32 v36, v43, v89
	v_add_u32_e32 v37, s11, v64
	v_lshlrev_b32_e32 v96, 16, v96
	v_cvt_pk_bf16_f32 v36, v36, s0
	v_cvt_f32_i32_e32 v37, v37
	v_lshlrev_b32_e32 v91, 16, v91
	global_store_short v[40:41], v36, off offset:32
	v_mul_f32_e32 v36, v43, v96
	v_fma_f32 v36, v42, v91, -v36
	v_cvt_pk_bf16_f32 v36, v36, s0
	global_store_short v[38:39], v36, off offset:1024
	v_mul_f32_e32 v36, v9, v37
	v_cvt_f64_f32_e32 v[36:37], v36
	v_mul_f64 v[38:39], v[36:37], s[0:1]
	v_rndne_f64_e32 v[38:39], v[38:39]
	v_fma_f64 v[36:37], v[36:37], s[0:1], -v[38:39]
	v_cvt_f32_f64_e32 v36, v[36:37]
	v_sin_f32_e32 v37, v36
	v_mul_f32_e32 v40, v42, v96
	v_cos_f32_e32 v36, v36
	v_fmac_f32_e32 v40, v43, v91
	v_lshlrev_b32_e32 v93, 16, v93
	v_cvt_pk_bf16_f32 v38, v40, s0
	v_lshlrev_b32_e32 v92, 16, v92
	global_store_short v[30:31], v38, off offset:32
	v_mul_f32_e32 v30, v37, v93
	v_fma_f32 v30, v36, v92, -v30
	v_cvt_pk_bf16_f32 v30, v30, s0
	global_store_short v[28:29], v30, off
	v_mul_f32_e32 v30, v36, v93
	v_fmac_f32_e32 v30, v37, v92
	v_add_u32_e32 v31, s11, v65
	v_lshlrev_b32_e32 v95, 16, v95
	v_cvt_pk_bf16_f32 v30, v30, s0
	v_cvt_f32_i32_e32 v31, v31
	v_lshlrev_b32_e32 v94, 16, v94
	global_store_short v[34:35], v30, off offset:32
	v_mul_f32_e32 v30, v37, v95
	v_fma_f32 v30, v36, v94, -v30
	v_cvt_pk_bf16_f32 v30, v30, s0
	global_store_short v[28:29], v30, off offset:1024
	v_mul_f32_e32 v28, v9, v31
	v_cvt_f64_f32_e32 v[28:29], v28
	v_mul_f64 v[30:31], v[28:29], s[0:1]
	v_rndne_f64_e32 v[30:31], v[30:31]
	v_fma_f64 v[28:29], v[28:29], s[0:1], -v[30:31]
	v_cvt_f32_f64_e32 v28, v[28:29]
	v_sin_f32_e32 v29, v28
	v_mul_f32_e32 v34, v36, v95
	v_cos_f32_e32 v28, v28
	v_fmac_f32_e32 v34, v37, v94
	v_lshlrev_b32_e32 v97, 16, v97
	v_cvt_pk_bf16_f32 v30, v34, s0
	v_lshlrev_b32_e32 v13, 16, v13
	global_store_short v[22:23], v30, off offset:32
	v_mul_f32_e32 v22, v29, v97
	v_fma_f32 v22, v28, v13, -v22
	v_cvt_pk_bf16_f32 v22, v22, s0
	global_store_short v[24:25], v22, off
	v_mul_f32_e32 v22, v28, v97
	v_fmac_f32_e32 v22, v29, v13
	v_cvt_pk_bf16_f32 v13, v22, s0
	v_add_u32_e32 v22, s11, v66
	v_cvt_f32_i32_e32 v22, v22
	s_waitcnt vmcnt(26)
	v_lshlrev_b32_e32 v102, 16, v102
	v_lshlrev_b32_e32 v98, 16, v98
	global_store_short v[26:27], v13, off offset:32
	v_mul_f32_e32 v13, v29, v102
	v_fma_f32 v13, v28, v98, -v13
	v_mul_f32_e32 v22, v9, v22
	v_cvt_pk_bf16_f32 v13, v13, s0
	v_cvt_f64_f32_e32 v[22:23], v22
	global_store_short v[24:25], v13, off offset:1024
	v_mul_f64 v[24:25], v[22:23], s[0:1]
	v_rndne_f64_e32 v[24:25], v[24:25]
	v_fma_f64 v[22:23], v[22:23], s[0:1], -v[24:25]
	v_cvt_f32_f64_e32 v22, v[22:23]
	v_sin_f32_e32 v23, v22
	v_mul_f32_e32 v13, v28, v102
	v_cos_f32_e32 v22, v22
	v_fmac_f32_e32 v13, v29, v98
	v_lshlrev_b32_e32 v99, 16, v99
	v_cvt_pk_bf16_f32 v13, v13, s0
	v_lshlrev_b32_e32 v101, 16, v101
	global_store_short v[14:15], v13, off offset:32
	v_mul_f32_e32 v13, v23, v99
	v_fma_f32 v13, v22, v101, -v13
	v_cvt_pk_bf16_f32 v13, v13, s0
	global_store_short v[20:21], v13, off
	v_mul_f32_e32 v13, v22, v99
	v_fmac_f32_e32 v13, v23, v101
	v_cvt_pk_bf16_f32 v13, v13, s0
	s_waitcnt vmcnt(29)
	v_lshlrev_b32_e32 v76, 16, v103
	global_store_short v[18:19], v13, off offset:32
	v_mul_f32_e32 v13, v23, v77
	v_fma_f32 v13, v22, v76, -v13
	v_cvt_pk_bf16_f32 v13, v13, s0
	global_store_short v[20:21], v13, off offset:1024
	v_mul_f32_e32 v13, v22, v77
	v_fmac_f32_e32 v13, v23, v76
	v_cvt_pk_bf16_f32 v13, v13, s0
	global_store_short v[16:17], v13, off offset:32
	v_add_u32_e32 v13, s13, v58
	v_mad_i64_i32 v[14:15], s[0:1], v13, s72, v[32:33]
	v_lshl_add_u64 v[14:15], v[10:11], 0, v[14:15]
	v_mov_b32_e32 v13, 0
	s_mov_b64 s[0:1], 0
	s_barrier
.LBB0_164:
	s_mov_b32 s0, 0x7601400
	s_mov_b32 s1, 0
	v_lshl_add_u64 v[16:17], v[14:15], 0, s[0:1]
	s_add_u32 s0, s0, 0x1e00
	global_load_ushort v108, v[16:17], off
	v_lshl_add_u64 v[18:19], v[14:15], 0, s[0:1]
	s_add_u32 s0, s0, 0x1e00
	global_load_ushort v109, v[18:19], off
	v_lshl_add_u64 v[16:17], v[14:15], 0, s[0:1]
	s_add_u32 s0, s0, 0x1e00
	global_load_ushort v110, v[16:17], off
	v_lshl_add_u64 v[18:19], v[14:15], 0, s[0:1]
	s_add_u32 s0, s0, 0x1e00
	global_load_ushort v111, v[18:19], off
	v_lshl_add_u64 v[16:17], v[14:15], 0, s[0:1]
	s_add_u32 s0, s0, 0x1e00
	global_load_ushort v112, v[16:17], off
	v_lshl_add_u64 v[18:19], v[14:15], 0, s[0:1]
	s_add_u32 s0, s0, 0x1e00
	global_load_ushort v113, v[18:19], off
	v_lshl_add_u64 v[16:17], v[14:15], 0, s[0:1]
	s_add_u32 s0, s0, 0x1e00
	global_load_ushort v114, v[16:17], off
	v_lshl_add_u64 v[18:19], v[14:15], 0, s[0:1]
	s_add_u32 s0, s0, 0x1e00
	global_load_ushort v115, v[18:19], off
	v_lshl_add_u64 v[16:17], v[14:15], 0, s[0:1]
	s_add_u32 s0, s0, 0x1e00
	global_load_ushort v116, v[16:17], off
	v_lshl_add_u64 v[18:19], v[14:15], 0, s[0:1]
	s_add_u32 s0, s0, 0x1e00
	global_load_ushort v117, v[18:19], off
	v_lshl_add_u64 v[16:17], v[14:15], 0, s[0:1]
	s_add_u32 s0, s0, 0x1e00
	global_load_ushort v118, v[16:17], off
	v_lshl_add_u64 v[18:19], v[14:15], 0, s[0:1]
	s_add_u32 s0, s0, 0x1e00
	global_load_ushort v119, v[18:19], off
	v_lshl_add_u64 v[16:17], v[14:15], 0, s[0:1]
	s_add_u32 s0, s0, 0x1e00
	global_load_ushort v120, v[16:17], off
	v_lshl_add_u64 v[18:19], v[14:15], 0, s[0:1]
	s_add_u32 s0, s0, 0x1e00
	global_load_ushort v121, v[18:19], off
	v_lshl_add_u64 v[16:17], v[14:15], 0, s[0:1]
	s_add_u32 s0, s0, 0x1e00
	global_load_ushort v122, v[16:17], off
	v_lshl_add_u64 v[18:19], v[14:15], 0, s[0:1]
	s_add_u32 s0, s0, 0x1e00
	global_load_ushort v123, v[18:19], off
	v_lshl_add_u64 v[16:17], v[14:15], 0, s[0:1]
	s_add_u32 s0, s0, 0x1e00
	global_load_ushort v124, v[16:17], off
	v_lshl_add_u64 v[18:19], v[14:15], 0, s[0:1]
	s_add_u32 s0, s0, 0x1e00
	global_load_ushort v125, v[18:19], off
	v_lshl_add_u64 v[16:17], v[14:15], 0, s[0:1]
	s_add_u32 s0, s0, 0x1e00
	global_load_ushort v126, v[16:17], off
	v_lshl_add_u64 v[18:19], v[14:15], 0, s[0:1]
	s_add_u32 s0, s0, 0x1e00
	global_load_ushort v127, v[18:19], off
	v_lshl_add_u64 v[16:17], v[14:15], 0, s[0:1]
	s_add_u32 s0, s0, 0x1e00
	global_load_ushort v128, v[16:17], off
	v_lshl_add_u64 v[18:19], v[14:15], 0, s[0:1]
	s_add_u32 s0, s0, 0x1e00
	global_load_ushort v129, v[18:19], off
	v_lshl_add_u64 v[16:17], v[14:15], 0, s[0:1]
	s_add_u32 s0, s0, 0x1e00
	global_load_ushort v130, v[16:17], off
	v_lshl_add_u64 v[18:19], v[14:15], 0, s[0:1]
	s_add_u32 s0, s0, 0x1e00
	global_load_ushort v131, v[18:19], off
	v_lshl_add_u64 v[16:17], v[14:15], 0, s[0:1]
	s_add_u32 s0, s0, 0x1e00
	global_load_ushort v132, v[16:17], off
	v_lshl_add_u64 v[18:19], v[14:15], 0, s[0:1]
	s_add_u32 s0, s0, 0x1e00
	global_load_ushort v133, v[18:19], off
	v_lshl_add_u64 v[16:17], v[14:15], 0, s[0:1]
	s_add_u32 s0, s0, 0x1e00
	global_load_ushort v134, v[16:17], off
	v_lshl_add_u64 v[18:19], v[14:15], 0, s[0:1]
	s_add_u32 s0, s0, 0x1e00
	global_load_ushort v135, v[18:19], off
	v_lshl_add_u64 v[16:17], v[14:15], 0, s[0:1]
	s_add_u32 s0, s0, 0x1e00
	global_load_ushort v136, v[16:17], off
	v_lshl_add_u64 v[18:19], v[14:15], 0, s[0:1]
	s_add_u32 s0, s0, 0x1e00
	global_load_ushort v137, v[18:19], off
	v_lshl_add_u64 v[16:17], v[14:15], 0, s[0:1]
	s_add_u32 s0, s0, 0x1e00
	global_load_ushort v138, v[16:17], off
	v_lshl_add_u64 v[18:19], v[14:15], 0, s[0:1]
	s_add_u32 s0, s0, 0x1e00
	global_load_ushort v139, v[18:19], off
	v_lshl_add_u64 v[16:17], v[14:15], 0, s[0:1]
	s_add_u32 s0, s0, 0x1e00
	global_load_ushort v184, v[16:17], off
	v_lshl_add_u64 v[18:19], v[14:15], 0, s[0:1]
	s_add_u32 s0, s0, 0x1e00
	global_load_ushort v185, v[18:19], off
	v_lshl_add_u64 v[16:17], v[14:15], 0, s[0:1]
	s_add_u32 s0, s0, 0x1e00
	global_load_ushort v186, v[16:17], off
	v_lshl_add_u64 v[18:19], v[14:15], 0, s[0:1]
	s_add_u32 s0, s0, 0x1e00
	global_load_ushort v187, v[18:19], off
	v_lshl_add_u64 v[16:17], v[14:15], 0, s[0:1]
	s_add_u32 s0, s0, 0x1e00
	global_load_ushort v188, v[16:17], off
	v_lshl_add_u64 v[18:19], v[14:15], 0, s[0:1]
	s_add_u32 s0, s0, 0x1e00
	global_load_ushort v189, v[18:19], off
	v_lshl_add_u64 v[16:17], v[14:15], 0, s[0:1]
	s_add_u32 s0, s0, 0x1e00
	global_load_ushort v190, v[16:17], off
	v_lshl_add_u64 v[18:19], v[14:15], 0, s[0:1]
	s_add_u32 s0, s0, 0x1e00
	global_load_ushort v191, v[18:19], off
	v_lshl_add_u64 v[16:17], v[14:15], 0, s[0:1]
	s_add_u32 s0, s0, 0x1e00
	global_load_ushort v192, v[16:17], off
	v_lshl_add_u64 v[18:19], v[14:15], 0, s[0:1]
	s_add_u32 s0, s0, 0x1e00
	global_load_ushort v193, v[18:19], off
	v_lshl_add_u64 v[16:17], v[14:15], 0, s[0:1]
	s_add_u32 s0, s0, 0x1e00
	global_load_ushort v194, v[16:17], off
	v_lshl_add_u64 v[18:19], v[14:15], 0, s[0:1]
	s_add_u32 s0, s0, 0x1e00
	global_load_ushort v195, v[18:19], off
	v_lshl_add_u64 v[16:17], v[14:15], 0, s[0:1]
	s_add_u32 s0, s0, 0x1e00
	global_load_ushort v196, v[16:17], off
	v_lshl_add_u64 v[18:19], v[14:15], 0, s[0:1]
	s_add_u32 s0, s0, 0x1e00
	global_load_ushort v197, v[18:19], off
	v_lshl_add_u64 v[16:17], v[14:15], 0, s[0:1]
	s_add_u32 s0, s0, 0x1e00
	global_load_ushort v198, v[16:17], off
	v_lshl_add_u64 v[18:19], v[14:15], 0, s[0:1]
	s_add_u32 s0, s0, 0x1e00
	global_load_ushort v199, v[18:19], off
	v_lshl_add_u64 v[16:17], v[14:15], 0, s[0:1]
	s_add_u32 s0, s0, 0x1e00
	global_load_ushort v200, v[16:17], off
	v_lshl_add_u64 v[18:19], v[14:15], 0, s[0:1]
	s_add_u32 s0, s0, 0x1e00
	global_load_ushort v201, v[18:19], off
	v_lshl_add_u64 v[16:17], v[14:15], 0, s[0:1]
	s_add_u32 s0, s0, 0x1e00
	global_load_ushort v202, v[16:17], off
	v_lshl_add_u64 v[18:19], v[14:15], 0, s[0:1]
	s_add_u32 s0, s0, 0x1e00
	global_load_ushort v203, v[18:19], off
	v_lshl_add_u64 v[16:17], v[14:15], 0, s[0:1]
	s_add_u32 s0, s0, 0x1e00
	global_load_ushort v204, v[16:17], off
	v_lshl_add_u64 v[18:19], v[14:15], 0, s[0:1]
	s_add_u32 s0, s0, 0x1e00
	global_load_ushort v205, v[18:19], off
	v_lshl_add_u64 v[16:17], v[14:15], 0, s[0:1]
	s_add_u32 s0, s0, 0x1e00
	global_load_ushort v206, v[16:17], off
	v_lshl_add_u64 v[18:19], v[14:15], 0, s[0:1]
	s_add_u32 s0, s0, 0x1e00
	global_load_ushort v207, v[18:19], off
	v_lshl_add_u64 v[16:17], v[14:15], 0, s[0:1]
	s_add_u32 s0, s0, 0x1e00
	global_load_ushort v208, v[16:17], off
	v_lshl_add_u64 v[18:19], v[14:15], 0, s[0:1]
	s_add_u32 s0, s0, 0x1e00
	global_load_ushort v209, v[18:19], off
	v_lshl_add_u64 v[16:17], v[14:15], 0, s[0:1]
	s_add_u32 s0, s0, 0x1e00
	global_load_ushort v230, v[16:17], off
	v_lshl_add_u64 v[18:19], v[14:15], 0, s[0:1]
	s_add_u32 s0, s0, 0x1e00
	global_load_ushort v231, v[18:19], off
	v_lshl_add_u64 v[16:17], v[14:15], 0, s[0:1]
	s_add_u32 s0, s0, 0x1e00
	global_load_ushort v232, v[16:17], off
	s_waitcnt vmcnt(60)
	v_lshlrev_b32_e32 v108, 16, v108
	v_add_f32_e32 v13, v13, v108
	v_lshl_add_u64 v[18:19], v[14:15], 0, s[0:1]
	s_add_u32 s0, s0, 0x1e00
	global_load_ushort v233, v[18:19], off
	s_waitcnt vmcnt(60)
	v_lshlrev_b32_e32 v109, 16, v109
	v_add_f32_e32 v13, v13, v109
	v_lshl_add_u64 v[16:17], v[14:15], 0, s[0:1]
	s_add_u32 s0, s0, 0x1e00
	global_load_ushort v234, v[16:17], off
	s_waitcnt vmcnt(60)
	v_lshlrev_b32_e32 v110, 16, v110
	v_add_f32_e32 v13, v13, v110
	v_lshl_add_u64 v[18:19], v[14:15], 0, s[0:1]
	s_add_u32 s0, s0, 0x1e00
	global_load_ushort v235, v[18:19], off
	s_waitcnt vmcnt(60)
	v_lshlrev_b32_e32 v111, 16, v111
	v_add_f32_e32 v13, v13, v111
	s_waitcnt vmcnt(59)
	v_lshlrev_b32_e32 v112, 16, v112
	v_add_f32_e32 v13, v13, v112
	s_waitcnt vmcnt(58)
	v_lshlrev_b32_e32 v113, 16, v113
	v_add_f32_e32 v13, v13, v113
	s_waitcnt vmcnt(57)
	v_lshlrev_b32_e32 v114, 16, v114
	v_add_f32_e32 v13, v13, v114
	s_waitcnt vmcnt(56)
	v_lshlrev_b32_e32 v115, 16, v115
	v_add_f32_e32 v13, v13, v115
	s_waitcnt vmcnt(55)
	v_lshlrev_b32_e32 v116, 16, v116
	v_add_f32_e32 v13, v13, v116
	s_waitcnt vmcnt(54)
	v_lshlrev_b32_e32 v117, 16, v117
	v_add_f32_e32 v13, v13, v117
	s_waitcnt vmcnt(53)
	v_lshlrev_b32_e32 v118, 16, v118
	v_add_f32_e32 v13, v13, v118
	s_waitcnt vmcnt(52)
	v_lshlrev_b32_e32 v119, 16, v119
	v_add_f32_e32 v13, v13, v119
	s_waitcnt vmcnt(51)
	v_lshlrev_b32_e32 v120, 16, v120
	v_add_f32_e32 v13, v13, v120
	s_waitcnt vmcnt(50)
	v_lshlrev_b32_e32 v121, 16, v121
	v_add_f32_e32 v13, v13, v121
	s_waitcnt vmcnt(49)
	v_lshlrev_b32_e32 v122, 16, v122
	v_add_f32_e32 v13, v13, v122
	s_waitcnt vmcnt(48)
	v_lshlrev_b32_e32 v123, 16, v123
	v_add_f32_e32 v13, v13, v123
	s_waitcnt vmcnt(47)
	v_lshlrev_b32_e32 v124, 16, v124
	v_add_f32_e32 v13, v13, v124
	s_waitcnt vmcnt(46)
	v_lshlrev_b32_e32 v125, 16, v125
	v_add_f32_e32 v13, v13, v125
	s_waitcnt vmcnt(45)
	v_lshlrev_b32_e32 v126, 16, v126
	v_add_f32_e32 v13, v13, v126
	s_waitcnt vmcnt(44)
	v_lshlrev_b32_e32 v127, 16, v127
	v_add_f32_e32 v13, v13, v127
	s_waitcnt vmcnt(43)
	v_lshlrev_b32_e32 v128, 16, v128
	v_add_f32_e32 v13, v13, v128
	s_waitcnt vmcnt(42)
	v_lshlrev_b32_e32 v129, 16, v129
	v_add_f32_e32 v13, v13, v129
	s_waitcnt vmcnt(41)
	v_lshlrev_b32_e32 v130, 16, v130
	v_add_f32_e32 v13, v13, v130
	s_waitcnt vmcnt(40)
	v_lshlrev_b32_e32 v131, 16, v131
	v_add_f32_e32 v13, v13, v131
	s_waitcnt vmcnt(39)
	v_lshlrev_b32_e32 v132, 16, v132
	v_add_f32_e32 v13, v13, v132
	s_waitcnt vmcnt(38)
	v_lshlrev_b32_e32 v133, 16, v133
	v_add_f32_e32 v13, v13, v133
	s_waitcnt vmcnt(37)
	v_lshlrev_b32_e32 v134, 16, v134
	v_add_f32_e32 v13, v13, v134
	s_waitcnt vmcnt(36)
	v_lshlrev_b32_e32 v135, 16, v135
	v_add_f32_e32 v13, v13, v135
	s_waitcnt vmcnt(35)
	v_lshlrev_b32_e32 v136, 16, v136
	v_add_f32_e32 v13, v13, v136
	s_waitcnt vmcnt(34)
	v_lshlrev_b32_e32 v137, 16, v137
	v_add_f32_e32 v13, v13, v137
	s_waitcnt vmcnt(33)
	v_lshlrev_b32_e32 v138, 16, v138
	v_add_f32_e32 v13, v13, v138
	s_waitcnt vmcnt(32)
	v_lshlrev_b32_e32 v139, 16, v139
	v_add_f32_e32 v13, v13, v139
	s_waitcnt vmcnt(31)
	v_lshlrev_b32_e32 v184, 16, v184
	v_add_f32_e32 v13, v13, v184
	s_waitcnt vmcnt(30)
	v_lshlrev_b32_e32 v185, 16, v185
	v_add_f32_e32 v13, v13, v185
	s_waitcnt vmcnt(29)
	v_lshlrev_b32_e32 v186, 16, v186
	v_add_f32_e32 v13, v13, v186
	s_waitcnt vmcnt(28)
	v_lshlrev_b32_e32 v187, 16, v187
	v_add_f32_e32 v13, v13, v187
	s_waitcnt vmcnt(27)
	v_lshlrev_b32_e32 v188, 16, v188
	v_add_f32_e32 v13, v13, v188
	s_waitcnt vmcnt(26)
	v_lshlrev_b32_e32 v189, 16, v189
	v_add_f32_e32 v13, v13, v189
	s_waitcnt vmcnt(25)
	v_lshlrev_b32_e32 v190, 16, v190
	v_add_f32_e32 v13, v13, v190
	s_waitcnt vmcnt(24)
	v_lshlrev_b32_e32 v191, 16, v191
	v_add_f32_e32 v13, v13, v191
	s_waitcnt vmcnt(23)
	v_lshlrev_b32_e32 v192, 16, v192
	v_add_f32_e32 v13, v13, v192
	s_waitcnt vmcnt(22)
	v_lshlrev_b32_e32 v193, 16, v193
	v_add_f32_e32 v13, v13, v193
	s_waitcnt vmcnt(21)
	v_lshlrev_b32_e32 v194, 16, v194
	v_add_f32_e32 v13, v13, v194
	s_waitcnt vmcnt(20)
	v_lshlrev_b32_e32 v195, 16, v195
	v_add_f32_e32 v13, v13, v195
	s_waitcnt vmcnt(19)
	v_lshlrev_b32_e32 v196, 16, v196
	v_add_f32_e32 v13, v13, v196
	s_waitcnt vmcnt(18)
	v_lshlrev_b32_e32 v197, 16, v197
	v_add_f32_e32 v13, v13, v197
	s_waitcnt vmcnt(17)
	v_lshlrev_b32_e32 v198, 16, v198
	v_add_f32_e32 v13, v13, v198
	s_waitcnt vmcnt(16)
	v_lshlrev_b32_e32 v199, 16, v199
	v_add_f32_e32 v13, v13, v199
	s_waitcnt vmcnt(15)
	v_lshlrev_b32_e32 v200, 16, v200
	v_add_f32_e32 v13, v13, v200
	s_waitcnt vmcnt(14)
	v_lshlrev_b32_e32 v201, 16, v201
	v_add_f32_e32 v13, v13, v201
	s_waitcnt vmcnt(13)
	v_lshlrev_b32_e32 v202, 16, v202
	v_add_f32_e32 v13, v13, v202
	s_waitcnt vmcnt(12)
	v_lshlrev_b32_e32 v203, 16, v203
	v_add_f32_e32 v13, v13, v203
	s_waitcnt vmcnt(11)
	v_lshlrev_b32_e32 v204, 16, v204
	v_add_f32_e32 v13, v13, v204
	s_waitcnt vmcnt(10)
	v_lshlrev_b32_e32 v205, 16, v205
	v_add_f32_e32 v13, v13, v205
	s_waitcnt vmcnt(9)
	v_lshlrev_b32_e32 v206, 16, v206
	v_add_f32_e32 v13, v13, v206
	s_waitcnt vmcnt(8)
	v_lshlrev_b32_e32 v207, 16, v207
	v_add_f32_e32 v13, v13, v207
	s_waitcnt vmcnt(7)
	v_lshlrev_b32_e32 v208, 16, v208
	v_add_f32_e32 v13, v13, v208
	s_waitcnt vmcnt(6)
	v_lshlrev_b32_e32 v209, 16, v209
	v_add_f32_e32 v13, v13, v209
	s_waitcnt vmcnt(5)
	v_lshlrev_b32_e32 v230, 16, v230
	v_add_f32_e32 v13, v13, v230
	s_waitcnt vmcnt(4)
	v_lshlrev_b32_e32 v231, 16, v231
	v_add_f32_e32 v13, v13, v231
	s_waitcnt vmcnt(3)
	v_lshlrev_b32_e32 v232, 16, v232
	v_add_f32_e32 v13, v13, v232
	s_waitcnt vmcnt(2)
	v_lshlrev_b32_e32 v233, 16, v233
	v_add_f32_e32 v13, v13, v233
	s_waitcnt vmcnt(1)
	v_lshlrev_b32_e32 v234, 16, v234
	v_add_f32_e32 v13, v13, v234
	s_waitcnt vmcnt(0)
	v_lshlrev_b32_e32 v235, 16, v235
	v_add_f32_e32 v13, v13, v235
	ds_write_b32 v59, v13
	s_waitcnt lgkmcnt(0)
	s_barrier
	s_and_saveexec_b64 s[0:1], s[6:7]
	s_cbranch_execz .LBB0_167
	ds_read2st64_b32 v[14:15], v59 offset1:2
	ds_read2st64_b32 v[16:17], v59 offset0:4 offset1:6
	s_and_b32 s17, s10, 0xffffff80
	s_lshl_b32 s15, s15, 5
	s_or_b32 s15, s15, s17
	s_waitcnt lgkmcnt(1)
	v_mov_b32_e32 v18, v14
	s_waitcnt lgkmcnt(0)
	v_mov_b32_e32 v19, v16
	v_mov_b32_e32 v16, v15
	s_or_b32 s14, s15, s14
	v_pk_add_f32 v[14:15], v[18:19], v[16:17]
	s_ashr_i32 s15, s14, 31
	v_add_f32_e32 v13, v14, v15
	s_lshl_b64 s[14:15], s[14:15], 9
	v_mul_f32_e32 v13, 0x3b800000, v13
	v_lshl_add_u64 v[14:15], v[4:5], 0, s[14:15]
	global_store_dword v[14:15], v13, off

.LBB0_168:
	v_add_u32_e32 v13, s0, v0
	v_ashrrev_i32_e32 v22, 4, v13
	v_mov_b64_e32 v[14:15], s[88:89]
	v_add_u32_e32 v13, 0x200, v13
	v_add_u32_e32 v16, s13, v22
	s_lshl_b32 s20, s16, 1
	v_ashrrev_i32_e32 v13, 4, v13
	v_mad_i64_i32 v[16:17], s[14:15], v16, s72, v[14:15]
	v_add_u32_e32 v18, s13, v13
	v_lshl_add_u64 v[16:17], v[16:17], 0, s[20:21]
	v_mad_i64_i32 v[14:15], s[14:15], v18, s72, v[14:15]
	v_lshl_add_u64 v[16:17], v[16:17], 0, v[2:3]
	v_lshl_add_u64 v[14:15], v[14:15], 0, s[20:21]
	v_add_co_u32_e32 v16, vcc, 0x1000, v16
	v_lshl_add_u64 v[14:15], v[14:15], 0, v[2:3]
	s_nop 0
	v_addc_co_u32_e32 v17, vcc, 0, v17, vcc
	v_add_co_u32_e32 v18, vcc, 0x1000, v14
	s_addk_i32 s0, 0x400
	s_nop 0
	v_addc_co_u32_e32 v19, vcc, 0, v15, vcc
	v_mad_u64_u32 v[144:145], s[14:15], v22, s64, v[6:7]
	v_mad_u64_u32 v[146:147], s[14:15], v13, s64, v[6:7]
	v_add_u32_e32 v13, s0, v0
	v_ashrrev_i32_e32 v22, 4, v13
	v_mov_b64_e32 v[14:15], s[88:89]
	v_add_u32_e32 v13, 0x200, v13
	v_add_u32_e32 v16, s13, v22
	s_lshl_b32 s20, s16, 1
	v_ashrrev_i32_e32 v13, 4, v13
	v_mad_i64_i32 v[16:17], s[14:15], v16, s72, v[14:15]
	v_add_u32_e32 v18, s13, v13
	v_lshl_add_u64 v[16:17], v[16:17], 0, s[20:21]
	v_mad_i64_i32 v[14:15], s[14:15], v18, s72, v[14:15]
	v_lshl_add_u64 v[16:17], v[16:17], 0, v[2:3]
	v_lshl_add_u64 v[14:15], v[14:15], 0, s[20:21]
	v_add_co_u32_e32 v16, vcc, 0x1000, v16
	v_lshl_add_u64 v[14:15], v[14:15], 0, v[2:3]
	s_nop 0
	v_addc_co_u32_e32 v17, vcc, 0, v17, vcc
	v_add_co_u32_e32 v18, vcc, 0x1000, v14
	s_addk_i32 s0, 0x400
	s_nop 0
	v_addc_co_u32_e32 v19, vcc, 0, v15, vcc
	v_mad_u64_u32 v[148:149], s[14:15], v22, s64, v[6:7]
	v_mad_u64_u32 v[150:151], s[14:15], v13, s64, v[6:7]
	v_add_u32_e32 v13, s0, v0
	v_ashrrev_i32_e32 v22, 4, v13
	v_mov_b64_e32 v[14:15], s[88:89]
	v_add_u32_e32 v13, 0x200, v13
	v_add_u32_e32 v16, s13, v22
	s_lshl_b32 s20, s16, 1
	v_ashrrev_i32_e32 v13, 4, v13
	v_mad_i64_i32 v[16:17], s[14:15], v16, s72, v[14:15]
	v_add_u32_e32 v18, s13, v13
	v_lshl_add_u64 v[16:17], v[16:17], 0, s[20:21]
	v_mad_i64_i32 v[14:15], s[14:15], v18, s72, v[14:15]
	v_lshl_add_u64 v[16:17], v[16:17], 0, v[2:3]
	v_lshl_add_u64 v[14:15], v[14:15], 0, s[20:21]
	v_add_co_u32_e32 v16, vcc, 0x1000, v16
	v_lshl_add_u64 v[14:15], v[14:15], 0, v[2:3]
	s_nop 0
	v_addc_co_u32_e32 v17, vcc, 0, v17, vcc
	v_add_co_u32_e32 v18, vcc, 0x1000, v14
	s_addk_i32 s0, 0x400
	s_nop 0
	v_addc_co_u32_e32 v19, vcc, 0, v15, vcc
	v_mad_u64_u32 v[152:153], s[14:15], v22, s64, v[6:7]
	v_mad_u64_u32 v[154:155], s[14:15], v13, s64, v[6:7]
	v_add_u32_e32 v13, s0, v0
	v_ashrrev_i32_e32 v22, 4, v13
	v_mov_b64_e32 v[14:15], s[88:89]
	v_add_u32_e32 v13, 0x200, v13
	v_add_u32_e32 v16, s13, v22
	s_lshl_b32 s20, s16, 1
	v_ashrrev_i32_e32 v13, 4, v13
	v_mad_i64_i32 v[16:17], s[14:15], v16, s72, v[14:15]
	v_add_u32_e32 v18, s13, v13
	v_lshl_add_u64 v[16:17], v[16:17], 0, s[20:21]
	v_mad_i64_i32 v[14:15], s[14:15], v18, s72, v[14:15]
	v_lshl_add_u64 v[16:17], v[16:17], 0, v[2:3]
	v_lshl_add_u64 v[14:15], v[14:15], 0, s[20:21]
	v_add_co_u32_e32 v16, vcc, 0x1000, v16
	v_lshl_add_u64 v[14:15], v[14:15], 0, v[2:3]
	s_nop 0
	v_addc_co_u32_e32 v17, vcc, 0, v17, vcc
	v_add_co_u32_e32 v18, vcc, 0x1000, v14
	s_addk_i32 s0, 0x400
	s_nop 0
	v_addc_co_u32_e32 v19, vcc, 0, v15, vcc
	v_mad_u64_u32 v[156:157], s[14:15], v22, s64, v[6:7]
	v_mad_u64_u32 v[158:159], s[14:15], v13, s64, v[6:7]
	s_waitcnt vmcnt(0)
	ds_write_b128 v144, v[236:239] offset:4096
	ds_write_b128 v146, v[240:243] offset:4096
	ds_write_b128 v148, v[244:247] offset:4096
	ds_write_b128 v150, v[248:251] offset:4096
	ds_write_b128 v152, v[160:163] offset:4096
	ds_write_b128 v154, v[164:167] offset:4096
	ds_write_b128 v156, v[168:171] offset:4096
	ds_write_b128 v158, v[140:143] offset:4096
	s_lshl_b32 s0, s12, 9
	s_or_b32 s0, s0, s16
	v_or_b32_e32 v14, s0, v7
	v_ashrrev_i32_e32 v15, 31, v14
	v_readlane_b32 s0, v254, 48
	v_lshlrev_b64 v[14:15], 14, v[14:15]
	v_readlane_b32 s1, v254, 49
	s_lshl_b32 s20, s11, 1
	s_waitcnt lgkmcnt(0)
	v_lshl_add_u64 v[14:15], s[0:1], 0, v[14:15]
	v_lshl_add_u64 v[14:15], v[14:15], 0, s[20:21]
	s_mov_b32 s0, 0
	s_barrier
